# second prologue phase: input-row conversion pairs moved from the 108 workgroups that run a shift-bias GEMV item to the other 148 workgroups
# baseline (speedup 1.0000x reference)
.LBB0_396:
	s_or_b64 exec, exec, s[0:1]
	s_lshr_b32 s0, s33, 6
	s_add_i32 s0, s0, s78
	s_mov_b64 s[60:61], s[14:15]
	s_mov_b32 s59, 0
	s_movk_i32 s58, 0x2fff
	s_cmpk_lt_i32 s2, 0x6c
	s_cselect_b32 s58, s0, s58
	s_cmpk_gt_i32 s0, 0x2fff
	s_cbranch_scc1 .LBB0_415
	v_and_b32_e32 v3, 63, v45
.Lmy_cv_setup:
	v_mov_b32_e32 v81, 0
	v_lshlrev_b32_e32 v6, 3, v3
	v_mov_b32_e32 v7, v81
	v_lshl_add_u64 v[8:9], s[40:41], 0, v[6:7]
	s_mov_b64 s[12:13], 0x6600000
	v_lshl_add_u64 v[86:87], v[8:9], 0, s[12:13]
	s_mov_b64 s[12:13], 0x9600000
	s_ashr_i32 s1, s0, 31
	s_lshl_b32 s10, s42, 4
	v_lshl_add_u64 v[88:89], v[8:9], 0, s[12:13]
	s_lshl_b64 s[12:13], s[0:1], 12
	v_lshlrev_b32_e32 v80, 2, v3
	v_lshlrev_b32_e32 v0, 4, v3
	v_mov_b32_e32 v1, v81
	s_add_u32 s12, s16, s12
	v_lshl_add_u64 v[82:83], s[14:15], 0, v[0:1]
	v_lshl_add_u64 v[0:1], s[40:41], 0, v[80:81]
	s_mov_b64 s[20:21], 0x600000
	s_addc_u32 s13, s17, s13
	s_lshl_b64 s[22:23], s[0:1], 6
	v_lshl_add_u64 v[84:85], v[0:1], 0, s[20:21]
	v_or_b32_e32 v0, 0x100, v80
	v_or_b32_e32 v2, 0x200, v80
	v_or_b32_e32 v4, 0x300, v80
	s_ashr_i32 s11, s10, 31
	v_lshl_add_u64 v[8:9], s[22:23], 0, v[80:81]
	s_lshl_b64 s[22:23], s[0:1], 11
	v_cmp_gt_u32_e64 s[4:5], 16, v3
	s_mov_b32 s9, 0
	v_cmp_eq_u32_e64 s[6:7], 0, v3
	s_lshl_b64 s[14:15], s[10:11], 12
	v_lshl_add_u64 v[90:91], v[8:9], 0, s[20:21]
	s_lshl_b64 s[20:21], s[10:11], 6
	v_or_b32_e32 v92, s22, v6
	v_mov_b32_e32 v93, s23
	s_lshl_b64 s[22:23], s[10:11], 11
	v_lshlrev_b32_e32 v81, 2, v0
	v_lshlrev_b32_e32 v94, 2, v2
	v_lshlrev_b32_e32 v95, 2, v4
	s_mov_b32 s1, 0x6600000
	s_mov_b32 s11, 0x9600000
	s_branch .LBB0_400

.LBB0_399:
	s_add_i32 s0, s0, s10
	s_add_u32 s12, s12, s14
	s_addc_u32 s13, s13, s15
	v_lshl_add_u64 v[90:91], v[90:91], 0, s[20:21]
	s_cmp_gt_i32 s0, s58
	v_lshl_add_u64 v[92:93], v[92:93], 0, s[22:23]
	s_cbranch_scc1 .LBB0_415

.LBB0_415:
	s_cmpk_lt_i32 s2, 0x6c
	s_cbranch_scc1 .Lmy_cv_done
	s_add_i32 s59, s59, 1
	s_lshr_b32 s0, s33, 6
	s_add_i32 s0, s0, s78
	s_sub_i32 s0, s0, 0x360
	s_cmp_eq_u32 s59, 1
	s_cbranch_scc0 .Lmy_cv_p2
	s_movk_i32 s58, 0x1ca0
	s_cmpk_lt_i32 s0, 0x360
	s_cselect_b32 s58, 0x1000, s58
	s_add_i32 s0, s0, s58
	s_branch .Lmy_cv_go
.Lmy_cv_p2:
	s_cmp_eq_u32 s59, 2
	s_cbranch_scc0 .Lmy_cv_done
	s_cmpk_ge_i32 s0, 0x220
	s_cbranch_scc1 .Lmy_cv_done
	s_add_i32 s0, s0, 0x2140
.Lmy_cv_go:
	s_mov_b32 s58, s0
	s_mov_b64 s[14:15], s[60:61]
	v_and_b32_e32 v3, 63, v228
	s_branch .Lmy_cv_setup
